# placement-independent variant: all seams are full grid barriers again (XCD-local FF1-to-FF2 seam removed), keeps write-through prologue without L2 write-back and the leader invalidate off the release
# baseline (speedup 1.0000x reference)
.LBB0_1061:
	s_andn2_saveexec_b64 s[4:5], s[10:11]
	s_cbranch_execz .LBB0_1081
	s_mov_b64 s[10:11], exec
	buffer_wbl2 sc1
	s_nop 0
	s_waitcnt lgkmcnt(0)
	s_waitcnt vmcnt(0)
	v_mbcnt_lo_u32_b32 v3, s10, 0
	v_mbcnt_hi_u32_b32 v3, s11, v3
	v_cmp_eq_u32_e32 vcc, 0, v3
	s_and_saveexec_b64 s[14:15], vcc
	s_cbranch_execz .LBB0_1064
	s_bcnt1_i32_b64 s4, s[10:11]
	v_mov_b32_e32 v4, s4
	v_readlane_b32 s4, v253, 42
	v_readlane_b32 s5, v253, 43
	s_nop 4
	global_atomic_add v4, v99, v4, s[4:5] sc0
.LBB0_1064:
	s_or_b64 exec, exec, s[14:15]
	s_waitcnt vmcnt(0)
	buffer_inv sc1
	v_readfirstlane_b32 s4, v4
	v_cvt_f32_u32_e32 v4, v2
	v_sub_u32_e32 v5, 0, v2
	v_add_u32_e32 v3, s4, v3
	v_readlane_b32 s4, v253, 44
	v_rcp_iflag_f32_e32 v4, v4
	v_readlane_b32 s5, v253, 45
	s_mov_b64 s[14:15], -1
	v_mul_f32_e32 v4, 0x4f7ffffe, v4
	v_cvt_u32_f32_e32 v4, v4
	v_mul_lo_u32 v5, v5, v4
	v_mul_hi_u32 v5, v4, v5
	v_add_u32_e32 v4, v4, v5
	v_mul_hi_u32 v4, v3, v4
	v_mul_lo_u32 v5, v4, v2
	v_sub_u32_e32 v5, v3, v5
	v_cmp_ge_u32_e32 vcc, v5, v2
	v_add_u32_e32 v6, 1, v4
	v_add_u32_e32 v3, 1, v3
	v_cndmask_b32_e32 v4, v4, v6, vcc
	v_sub_u32_e32 v6, v5, v2
	v_cndmask_b32_e32 v5, v5, v6, vcc
	v_cmp_ge_u32_e32 vcc, v5, v2
	v_add_u32_e32 v5, 1, v4
	s_nop 0
	v_cndmask_b32_e32 v4, v4, v5, vcc
	v_mul_lo_u32 v5, v2, v4
	v_add_u32_e32 v2, v5, v2
	v_cmp_ne_u32_e32 vcc, v3, v2
	v_mov_b64_e32 v[2:3], s[4:5]
	s_and_saveexec_b64 s[10:11], vcc
	s_cbranch_execz .LBB0_1076
	v_readlane_b32 s4, v253, 44
	v_readlane_b32 s5, v253, 45
	s_mov_b64 s[20:21], 0
	s_nop 3
	global_load_dword v2, v99, s[4:5] sc1
	s_waitcnt vmcnt(0)
	v_cmp_eq_u32_e32 vcc, v2, v4
	s_and_saveexec_b64 s[14:15], vcc
	s_cbranch_execz .LBB0_1075
	s_mov_b32 s27, 1
	s_branch .LBB0_1068

.LBB0_1078:
	s_or_b64 exec, exec, s[10:11]
	s_mov_b64 s[10:11], exec
	v_mbcnt_lo_u32_b32 v2, s10, 0
	v_mbcnt_hi_u32_b32 v2, s11, v2
	v_cmp_eq_u32_e32 vcc, 0, v2
	s_nop 0
	s_nop 0
	s_and_saveexec_b64 s[14:15], vcc
	s_cbranch_execz .LBB0_1080
	s_bcnt1_i32_b64 s4, s[10:11]
	v_mov_b32_e32 v2, s4
	v_readlane_b32 s4, v253, 40
	v_readlane_b32 s5, v253, 41
	s_nop 4
	global_atomic_add v99, v2, s[4:5]
